# non-temporal policy also on the A'/x stores of the mixer and FFN-down residual epilogues; on top of v64
# baseline (speedup 1.0000x reference)
.Lxr2_0:
.LBB0_1058:
	v_lshlrev_b64 v[216:217], 11, v[178:179]
	v_lshl_add_u64 v[182:183], v[216:217], 0, v[196:197]
	s_waitcnt vmcnt(0) lgkmcnt(0)
	v_pk_fma_f32 v[192:193], v[142:143], v[110:111], v[170:171]
	v_lshlrev_b64 v[142:143], 1, v[182:183]
	v_pk_fma_f32 v[190:191], v[144:145], v[112:113], v[172:173]
	v_pk_fma_f32 v[174:175], v[138:139], v[106:107], v[174:175]
	v_cvt_pk_bf16_f32 v138, v192, v193
	v_cvt_pk_bf16_f32 v139, v190, v191
	v_lshl_add_u64 v[144:145], s[12:13], 0, v[142:143]
	v_pk_fma_f32 v[176:177], v[140:141], v[108:109], v[176:177]
	v_cvt_pk_bf16_f32 v140, v174, v175
	v_lshl_add_u64 v[142:143], s[18:19], 0, v[142:143]
	v_cvt_pk_bf16_f32 v141, v176, v177
	v_lshlrev_b64 v[218:219], 11, v[200:201]
	v_pk_mul_f32 v[144:145], v[100:101], v[176:177]
	v_pk_mul_f32 v[138:139], v[102:103], v[192:193]
	v_pk_mul_f32 v[140:141], v[104:105], v[190:191]
	v_cvt_pk_bf16_f32 v138, v138, v139
	v_pk_mul_f32 v[170:171], v[98:99], v[174:175]
	v_cvt_pk_bf16_f32 v139, v140, v141
	v_pk_fma_f32 v[172:173], v[134:135], v[110:111], v[162:163]
	v_cvt_pk_bf16_f32 v140, v170, v171
	v_cvt_pk_bf16_f32 v141, v144, v145
	flat_store_dwordx4 v[142:143], v[138:141] nt
	v_pk_fma_f32 v[170:171], v[136:137], v[112:113], v[164:165]
	v_pk_fma_f32 v[166:167], v[130:131], v[106:107], v[166:167]
	v_lshl_add_u64 v[138:139], v[218:219], 0, v[196:197]
	v_lshlrev_b64 v[134:135], 1, v[138:139]
	v_cvt_pk_bf16_f32 v130, v172, v173
	v_cvt_pk_bf16_f32 v131, v170, v171
	v_lshl_add_u64 v[136:137], s[12:13], 0, v[134:135]
	v_pk_fma_f32 v[168:169], v[132:133], v[108:109], v[168:169]
	v_cvt_pk_bf16_f32 v132, v166, v167
	v_lshl_add_u64 v[134:135], s[18:19], 0, v[134:135]
	v_cvt_pk_bf16_f32 v133, v168, v169
	v_lshlrev_b64 v[220:221], 11, v[198:199]
	v_pk_mul_f32 v[136:137], v[100:101], v[168:169]
	v_pk_mul_f32 v[130:131], v[102:103], v[172:173]
	v_pk_mul_f32 v[132:133], v[104:105], v[170:171]
	v_cvt_pk_bf16_f32 v130, v130, v131
	v_pk_mul_f32 v[138:139], v[98:99], v[166:167]
	v_cvt_pk_bf16_f32 v131, v132, v133
	v_pk_fma_f32 v[164:165], v[126:127], v[110:111], v[154:155]
	v_cvt_pk_bf16_f32 v132, v138, v139
	v_cvt_pk_bf16_f32 v133, v136, v137
	flat_store_dwordx4 v[134:135], v[130:133] nt
	v_pk_fma_f32 v[162:163], v[128:129], v[112:113], v[156:157]
	v_pk_fma_f32 v[158:159], v[122:123], v[106:107], v[158:159]
	v_lshl_add_u64 v[130:131], v[220:221], 0, v[196:197]
	v_lshlrev_b64 v[126:127], 1, v[130:131]
	v_cvt_pk_bf16_f32 v122, v164, v165
	v_cvt_pk_bf16_f32 v123, v162, v163
	v_lshl_add_u64 v[128:129], s[12:13], 0, v[126:127]
	v_pk_fma_f32 v[156:157], v[124:125], v[108:109], v[160:161]
	v_cvt_pk_bf16_f32 v124, v158, v159
	v_lshl_add_u64 v[126:127], s[18:19], 0, v[126:127]
	v_cvt_pk_bf16_f32 v125, v156, v157
	v_lshlrev_b64 v[222:223], 11, v[194:195]
	v_pk_mul_f32 v[128:129], v[100:101], v[156:157]
	v_pk_mul_f32 v[122:123], v[102:103], v[164:165]
	v_pk_mul_f32 v[124:125], v[104:105], v[162:163]
	v_cvt_pk_bf16_f32 v122, v122, v123
	v_pk_mul_f32 v[130:131], v[98:99], v[158:159]
	v_cvt_pk_bf16_f32 v123, v124, v125
	v_pk_fma_f32 v[154:155], v[118:119], v[110:111], v[146:147]
	v_cvt_pk_bf16_f32 v124, v130, v131
	v_cvt_pk_bf16_f32 v125, v128, v129
	flat_store_dwordx4 v[126:127], v[122:125] nt
	v_pk_fma_f32 v[146:147], v[116:117], v[108:109], v[152:153]
	v_add_u32_e32 v152, 0x80, v178
	v_lshl_add_u64 v[122:123], v[222:223], 0, v[196:197]
	v_lshlrev_b64 v[118:119], 1, v[122:123]
	v_pk_fma_f32 v[148:149], v[120:121], v[112:113], v[148:149]
	v_pk_fma_f32 v[150:151], v[114:115], v[106:107], v[150:151]
	v_cvt_pk_bf16_f32 v114, v154, v155
	v_cvt_pk_bf16_f32 v115, v148, v149
	v_lshl_add_u64 v[120:121], s[12:13], 0, v[118:119]
	v_cvt_pk_bf16_f32 v116, v150, v151
	v_cvt_pk_bf16_f32 v117, v146, v147
	v_ashrrev_i32_e32 v153, 31, v152
	v_lshl_add_u64 v[118:119], s[18:19], 0, v[118:119]
	s_and_b64 vcc, exec, s[8:9]
	v_pk_mul_f32 v[116:117], v[104:105], v[148:149]
	v_pk_mul_f32 v[114:115], v[102:103], v[154:155]
	v_lshlrev_b64 v[224:225], 13, v[152:153]
	v_add_u32_e32 v206, 0x90, v178
	v_add_u32_e32 v204, 0xa0, v178
	v_add_u32_e32 v202, 0xb0, v178
	v_pk_mul_f32 v[120:121], v[100:101], v[146:147]
	v_pk_mul_f32 v[122:123], v[98:99], v[150:151]
	v_cvt_pk_bf16_f32 v114, v114, v115
	v_cvt_pk_bf16_f32 v115, v116, v117
	s_nop 0
	v_cvt_pk_bf16_f32 v116, v122, v123
	v_cvt_pk_bf16_f32 v117, v120, v121
	flat_store_dwordx4 v[118:119], v[114:117] nt
	s_cbranch_vccnz .LBB0_1066
	s_nop 0
	v_lshl_add_u64 v[114:115], v[188:189], 0, v[224:225]
	v_ashrrev_i32_e32 v207, 31, v206
	global_load_dwordx4 v[142:145], v[114:115], off offset:16
	global_load_dwordx4 v[138:141], v[114:115], off
	v_lshlrev_b64 v[114:115], 13, v[206:207]
	v_lshl_add_u64 v[114:115], v[188:189], 0, v[114:115]
	v_ashrrev_i32_e32 v205, 31, v204
	global_load_dwordx4 v[134:137], v[114:115], off offset:16
	global_load_dwordx4 v[130:133], v[114:115], off
	v_lshlrev_b64 v[114:115], 13, v[204:205]
	v_lshl_add_u64 v[114:115], v[188:189], 0, v[114:115]
	v_ashrrev_i32_e32 v203, 31, v202
	global_load_dwordx4 v[126:129], v[114:115], off offset:16
	global_load_dwordx4 v[122:125], v[114:115], off
	v_lshlrev_b64 v[114:115], 13, v[202:203]
	v_lshl_add_u64 v[114:115], v[188:189], 0, v[114:115]
	global_load_dwordx4 v[118:121], v[114:115], off offset:16
	s_nop 0
	global_load_dwordx4 v[114:117], v[114:115], off
	v_lshlrev_b64 v[232:233], 12, v[152:153]
	s_cbranch_execnz .LBB0_1061

.Lxr2_1:
.LBB0_1061:
	v_lshlrev_b64 v[226:227], 11, v[152:153]
	v_lshl_add_u64 v[160:161], v[226:227], 0, v[196:197]
	s_waitcnt vmcnt(0)
	v_pk_fma_f32 v[152:153], v[94:95], v[110:111], v[138:139]
	v_lshlrev_b64 v[94:95], 1, v[160:161]
	v_pk_fma_f32 v[140:141], v[96:97], v[112:113], v[140:141]
	v_pk_fma_f32 v[138:139], v[92:93], v[108:109], v[144:145]
	v_pk_fma_f32 v[144:145], v[90:91], v[106:107], v[142:143]
	v_cvt_pk_bf16_f32 v90, v152, v153
	v_cvt_pk_bf16_f32 v91, v140, v141
	v_lshl_add_u64 v[96:97], s[12:13], 0, v[94:95]
	v_cvt_pk_bf16_f32 v92, v144, v145
	v_cvt_pk_bf16_f32 v93, v138, v139
	v_lshl_add_u64 v[94:95], s[18:19], 0, v[94:95]
	v_lshlrev_b64 v[228:229], 11, v[206:207]
	v_pk_mul_f32 v[90:91], v[102:103], v[152:153]
	v_pk_mul_f32 v[92:93], v[104:105], v[140:141]
	v_cvt_pk_bf16_f32 v90, v90, v91
	v_pk_mul_f32 v[96:97], v[100:101], v[138:139]
	v_cvt_pk_bf16_f32 v91, v92, v93
	v_pk_mul_f32 v[142:143], v[98:99], v[144:145]
	v_pk_fma_f32 v[160:161], v[86:87], v[110:111], v[130:131]
	v_cvt_pk_bf16_f32 v92, v142, v143
	v_cvt_pk_bf16_f32 v93, v96, v97
	flat_store_dwordx4 v[94:95], v[90:93] nt
	v_pk_fma_f32 v[142:143], v[88:89], v[112:113], v[132:133]
	v_pk_fma_f32 v[134:135], v[82:83], v[106:107], v[134:135]
	v_lshl_add_u64 v[90:91], v[228:229], 0, v[196:197]
	v_lshlrev_b64 v[86:87], 1, v[90:91]
	v_cvt_pk_bf16_f32 v82, v160, v161
	v_cvt_pk_bf16_f32 v83, v142, v143
	v_lshl_add_u64 v[88:89], s[12:13], 0, v[86:87]
	v_pk_fma_f32 v[136:137], v[84:85], v[108:109], v[136:137]
	v_cvt_pk_bf16_f32 v84, v134, v135
	v_lshl_add_u64 v[86:87], s[18:19], 0, v[86:87]
	v_cvt_pk_bf16_f32 v85, v136, v137
	v_lshlrev_b64 v[230:231], 11, v[204:205]
	v_pk_mul_f32 v[88:89], v[100:101], v[136:137]
	v_pk_mul_f32 v[82:83], v[102:103], v[160:161]
	v_pk_mul_f32 v[84:85], v[104:105], v[142:143]
	v_cvt_pk_bf16_f32 v82, v82, v83
	v_pk_mul_f32 v[90:91], v[98:99], v[134:135]
	v_cvt_pk_bf16_f32 v83, v84, v85
	v_pk_fma_f32 v[132:133], v[78:79], v[110:111], v[122:123]
	v_cvt_pk_bf16_f32 v84, v90, v91
	v_cvt_pk_bf16_f32 v85, v88, v89
	flat_store_dwordx4 v[86:87], v[82:85] nt
	v_pk_fma_f32 v[130:131], v[80:81], v[112:113], v[124:125]
	v_pk_fma_f32 v[126:127], v[74:75], v[106:107], v[126:127]
	v_lshl_add_u64 v[82:83], v[230:231], 0, v[196:197]
	v_lshlrev_b64 v[78:79], 1, v[82:83]
	v_cvt_pk_bf16_f32 v74, v132, v133
	v_cvt_pk_bf16_f32 v75, v130, v131
	v_lshl_add_u64 v[80:81], s[12:13], 0, v[78:79]
	v_pk_fma_f32 v[124:125], v[76:77], v[108:109], v[128:129]
	v_cvt_pk_bf16_f32 v76, v126, v127
	v_lshl_add_u64 v[78:79], s[18:19], 0, v[78:79]
	v_cvt_pk_bf16_f32 v77, v124, v125
	v_lshlrev_b64 v[128:129], 11, v[202:203]
	v_pk_mul_f32 v[80:81], v[100:101], v[124:125]
	v_pk_mul_f32 v[74:75], v[102:103], v[132:133]
	v_pk_mul_f32 v[76:77], v[104:105], v[130:131]
	v_cvt_pk_bf16_f32 v74, v74, v75
	v_pk_mul_f32 v[82:83], v[98:99], v[126:127]
	v_cvt_pk_bf16_f32 v75, v76, v77
	v_pk_fma_f32 v[122:123], v[70:71], v[110:111], v[114:115]
	v_cvt_pk_bf16_f32 v76, v82, v83
	v_cvt_pk_bf16_f32 v77, v80, v81
	flat_store_dwordx4 v[78:79], v[74:77] nt
	v_pk_fma_f32 v[116:117], v[72:73], v[112:113], v[116:117]
	v_pk_fma_f32 v[114:115], v[68:69], v[108:109], v[120:121]
	v_lshl_add_u64 v[74:75], v[128:129], 0, v[196:197]
	v_lshlrev_b64 v[70:71], 1, v[74:75]
	v_pk_fma_f32 v[118:119], v[66:67], v[106:107], v[118:119]
	v_cvt_pk_bf16_f32 v66, v122, v123
	v_cvt_pk_bf16_f32 v67, v116, v117
	v_lshl_add_u64 v[72:73], s[12:13], 0, v[70:71]
	v_cvt_pk_bf16_f32 v68, v118, v119
	v_cvt_pk_bf16_f32 v69, v114, v115
	v_lshl_add_u64 v[70:71], s[18:19], 0, v[70:71]
	v_pk_mul_f32 v[72:73], v[100:101], v[114:115]
	v_pk_mul_f32 v[68:69], v[104:105], v[116:117]
	v_pk_mul_f32 v[66:67], v[102:103], v[122:123]
	v_pk_mul_f32 v[74:75], v[98:99], v[118:119]
	v_cvt_pk_bf16_f32 v66, v66, v67
	v_cvt_pk_bf16_f32 v67, v68, v69
	s_and_b64 vcc, exec, s[8:9]
	v_cvt_pk_bf16_f32 v68, v74, v75
	v_cvt_pk_bf16_f32 v69, v72, v73
	flat_store_dwordx4 v[70:71], v[66:69] nt
	flat_load_dwordx4 v[78:81], v[208:209] offset:512
	flat_load_dwordx4 v[74:77], v[208:209] offset:528
	s_nop 0
	flat_load_dwordx4 v[70:73], v[210:211] offset:512
	flat_load_dwordx4 v[66:69], v[210:211] offset:528
	s_cbranch_vccnz .LBB0_1067
	v_lshl_add_u64 v[82:83], v[188:189], 0, v[212:213]
	global_load_dwordx4 v[110:113], v[82:83], off offset:528
	global_load_dwordx4 v[106:109], v[82:83], off offset:512
	v_lshlrev_b64 v[82:83], 13, v[200:201]
	v_lshl_add_u64 v[82:83], v[188:189], 0, v[82:83]
	global_load_dwordx4 v[102:105], v[82:83], off offset:528
	global_load_dwordx4 v[98:101], v[82:83], off offset:512
	v_lshlrev_b64 v[82:83], 13, v[198:199]
	v_lshl_add_u64 v[82:83], v[188:189], 0, v[82:83]
	global_load_dwordx4 v[94:97], v[82:83], off offset:528
	global_load_dwordx4 v[90:93], v[82:83], off offset:512
	v_lshlrev_b64 v[82:83], 13, v[194:195]
	v_lshl_add_u64 v[82:83], v[188:189], 0, v[82:83]
	global_load_dwordx4 v[86:89], v[82:83], off offset:528
	s_nop 0
	global_load_dwordx4 v[82:85], v[82:83], off offset:512
	s_mov_b64 s[30:31], 0
	s_branch .LBB0_1068

.Lxr2_2:
.LBB0_1070:
	v_lshl_add_u64 v[182:183], v[216:217], 0, v[120:121]
	s_waitcnt vmcnt(0) lgkmcnt(0)
	v_pk_fma_f32 v[198:199], v[62:63], v[78:79], v[106:107]
	v_lshlrev_b64 v[62:63], 1, v[182:183]
	v_pk_fma_f32 v[194:195], v[64:65], v[80:81], v[108:109]
	v_pk_fma_f32 v[110:111], v[58:59], v[74:75], v[110:111]
	v_cvt_pk_bf16_f32 v58, v198, v199
	v_cvt_pk_bf16_f32 v59, v194, v195
	v_lshl_add_u64 v[64:65], s[12:13], 0, v[62:63]
	v_pk_fma_f32 v[112:113], v[60:61], v[76:77], v[112:113]
	v_cvt_pk_bf16_f32 v60, v110, v111
	v_lshl_add_u64 v[62:63], s[18:19], 0, v[62:63]
	v_cvt_pk_bf16_f32 v61, v112, v113
	v_pk_mul_f32 v[64:65], v[68:69], v[112:113]
	v_pk_mul_f32 v[106:107], v[66:67], v[110:111]
	v_pk_mul_f32 v[58:59], v[70:71], v[198:199]
	v_pk_mul_f32 v[60:61], v[72:73], v[194:195]
	v_cvt_pk_bf16_f32 v58, v58, v59
	v_pk_fma_f32 v[108:109], v[54:55], v[78:79], v[98:99]
	v_cvt_pk_bf16_f32 v59, v60, v61
	v_cvt_pk_bf16_f32 v60, v106, v107
	v_cvt_pk_bf16_f32 v61, v64, v65
	flat_store_dwordx4 v[62:63], v[58:61] nt
	v_pk_fma_f32 v[106:107], v[56:57], v[80:81], v[100:101]
	v_pk_fma_f32 v[102:103], v[50:51], v[74:75], v[102:103]
	v_lshl_add_u64 v[58:59], v[218:219], 0, v[120:121]
	v_lshlrev_b64 v[54:55], 1, v[58:59]
	v_cvt_pk_bf16_f32 v50, v108, v109
	v_cvt_pk_bf16_f32 v51, v106, v107
	v_lshl_add_u64 v[56:57], s[12:13], 0, v[54:55]
	v_pk_fma_f32 v[104:105], v[52:53], v[76:77], v[104:105]
	v_cvt_pk_bf16_f32 v52, v102, v103
	v_lshl_add_u64 v[54:55], s[18:19], 0, v[54:55]
	v_cvt_pk_bf16_f32 v53, v104, v105
	v_pk_mul_f32 v[56:57], v[68:69], v[104:105]
	v_pk_mul_f32 v[58:59], v[66:67], v[102:103]
	v_pk_mul_f32 v[50:51], v[70:71], v[108:109]
	v_pk_mul_f32 v[52:53], v[72:73], v[106:107]
	v_cvt_pk_bf16_f32 v50, v50, v51
	v_pk_fma_f32 v[100:101], v[46:47], v[78:79], v[90:91]
	v_cvt_pk_bf16_f32 v51, v52, v53
	v_cvt_pk_bf16_f32 v52, v58, v59
	v_cvt_pk_bf16_f32 v53, v56, v57
	flat_store_dwordx4 v[54:55], v[50:53] nt
	v_pk_fma_f32 v[98:99], v[48:49], v[80:81], v[92:93]
	v_pk_fma_f32 v[94:95], v[42:43], v[74:75], v[94:95]
	v_lshl_add_u64 v[50:51], v[220:221], 0, v[120:121]
	v_lshlrev_b64 v[46:47], 1, v[50:51]
	v_cvt_pk_bf16_f32 v42, v100, v101
	v_cvt_pk_bf16_f32 v43, v98, v99
	v_lshl_add_u64 v[48:49], s[12:13], 0, v[46:47]
	v_pk_fma_f32 v[92:93], v[44:45], v[76:77], v[96:97]
	v_cvt_pk_bf16_f32 v44, v94, v95
	v_lshl_add_u64 v[46:47], s[18:19], 0, v[46:47]
	v_cvt_pk_bf16_f32 v45, v92, v93
	v_pk_mul_f32 v[48:49], v[68:69], v[92:93]
	v_pk_mul_f32 v[50:51], v[66:67], v[94:95]
	v_pk_mul_f32 v[42:43], v[70:71], v[100:101]
	v_pk_mul_f32 v[44:45], v[72:73], v[98:99]
	v_cvt_pk_bf16_f32 v42, v42, v43
	v_pk_fma_f32 v[90:91], v[38:39], v[78:79], v[82:83]
	v_cvt_pk_bf16_f32 v43, v44, v45
	v_cvt_pk_bf16_f32 v44, v50, v51
	v_cvt_pk_bf16_f32 v45, v48, v49
	flat_store_dwordx4 v[46:47], v[42:45] nt
	v_pk_fma_f32 v[84:85], v[40:41], v[80:81], v[84:85]
	v_pk_fma_f32 v[82:83], v[36:37], v[76:77], v[88:89]
	v_lshl_add_u64 v[42:43], v[222:223], 0, v[120:121]
	v_lshlrev_b64 v[38:39], 1, v[42:43]
	v_pk_fma_f32 v[86:87], v[34:35], v[74:75], v[86:87]
	v_cvt_pk_bf16_f32 v34, v90, v91
	v_cvt_pk_bf16_f32 v35, v84, v85
	v_lshl_add_u64 v[40:41], s[12:13], 0, v[38:39]
	v_cvt_pk_bf16_f32 v36, v86, v87
	v_cvt_pk_bf16_f32 v37, v82, v83
	v_lshl_add_u64 v[38:39], s[18:19], 0, v[38:39]
	s_and_b64 vcc, exec, s[8:9]
	v_pk_mul_f32 v[36:37], v[72:73], v[84:85]
	v_pk_mul_f32 v[34:35], v[70:71], v[90:91]
	v_pk_mul_f32 v[40:41], v[68:69], v[82:83]
	v_pk_mul_f32 v[42:43], v[66:67], v[86:87]
	v_cvt_pk_bf16_f32 v34, v34, v35
	v_cvt_pk_bf16_f32 v35, v36, v37
	s_nop 0
	v_cvt_pk_bf16_f32 v36, v42, v43
	v_cvt_pk_bf16_f32 v37, v40, v41
	flat_store_dwordx4 v[38:39], v[34:37] nt
	s_cbranch_vccnz .LBB0_1092
	s_nop 0
	v_lshl_add_u64 v[34:35], v[188:189], 0, v[224:225]
	global_load_dwordx4 v[62:65], v[34:35], off offset:528
	global_load_dwordx4 v[58:61], v[34:35], off offset:512
	v_lshlrev_b64 v[34:35], 13, v[206:207]
	v_lshl_add_u64 v[34:35], v[188:189], 0, v[34:35]
	global_load_dwordx4 v[54:57], v[34:35], off offset:528
	global_load_dwordx4 v[50:53], v[34:35], off offset:512
	v_lshlrev_b64 v[34:35], 13, v[204:205]
	v_lshl_add_u64 v[34:35], v[188:189], 0, v[34:35]
	global_load_dwordx4 v[46:49], v[34:35], off offset:528
	global_load_dwordx4 v[42:45], v[34:35], off offset:512
	v_lshlrev_b64 v[34:35], 13, v[202:203]
	v_lshl_add_u64 v[34:35], v[188:189], 0, v[34:35]
	global_load_dwordx4 v[38:41], v[34:35], off offset:528
	s_nop 0
	global_load_dwordx4 v[34:37], v[34:35], off offset:512
	s_cbranch_execnz .LBB0_1073

.Lxr2_3:
.LBB0_1073:
	v_mul_f32_e32 v88, v192, v192
	v_mul_f32_e32 v89, v190, v190
	v_fmac_f32_e32 v88, v193, v193
	v_fmac_f32_e32 v89, v191, v191
	v_add_f32_e32 v88, v89, v88
	v_mul_f32_e32 v89, v174, v174
	v_mul_f32_e32 v96, v177, v177
	v_fmac_f32_e32 v89, v175, v175
	v_fmac_f32_e32 v96, v176, v176
	v_add_f32_e32 v89, v96, v89
	v_add_f32_e32 v88, v89, v88
	v_mul_f32_e32 v89, v198, v198
	v_mul_f32_e32 v96, v194, v194
	v_fmac_f32_e32 v89, v199, v199
	v_fmac_f32_e32 v96, v195, v195
	v_add_f32_e32 v89, v96, v89
	v_mul_f32_e32 v96, v110, v110
	v_mul_f32_e32 v97, v113, v113
	v_fmac_f32_e32 v96, v111, v111
	v_fmac_f32_e32 v97, v112, v112
	v_add_f32_e32 v96, v97, v96
	v_add_f32_e32 v89, v96, v89
	v_add_f32_e32 v96, v88, v89
	v_lshl_add_u64 v[88:89], v[226:227], 0, v[120:121]
	s_waitcnt vmcnt(0)
	v_pk_fma_f32 v[26:27], v[26:27], v[74:75], v[62:63]
	v_lshlrev_b64 v[62:63], 1, v[88:89]
	v_pk_fma_f32 v[32:33], v[32:33], v[80:81], v[60:61]
	v_pk_fma_f32 v[30:31], v[30:31], v[78:79], v[58:59]
	v_pk_fma_f32 v[28:29], v[28:29], v[76:77], v[64:65]
	v_cvt_pk_bf16_f32 v58, v30, v31
	v_cvt_pk_bf16_f32 v59, v32, v33
	v_lshl_add_u64 v[64:65], s[12:13], 0, v[62:63]
	v_cvt_pk_bf16_f32 v60, v26, v27
	v_cvt_pk_bf16_f32 v61, v28, v29
	v_lshl_add_u64 v[62:63], s[18:19], 0, v[62:63]
	v_pk_mul_f32 v[64:65], v[68:69], v[28:29]
	v_pk_mul_f32 v[58:59], v[70:71], v[30:31]
	v_pk_mul_f32 v[60:61], v[72:73], v[32:33]
	v_cvt_pk_bf16_f32 v58, v58, v59
	v_pk_mul_f32 v[88:89], v[66:67], v[26:27]
	v_cvt_pk_bf16_f32 v59, v60, v61
	v_pk_fma_f32 v[18:19], v[18:19], v[74:75], v[54:55]
	v_cvt_pk_bf16_f32 v60, v88, v89
	v_cvt_pk_bf16_f32 v61, v64, v65
	flat_store_dwordx4 v[62:63], v[58:61] nt
	v_pk_fma_f32 v[24:25], v[24:25], v[80:81], v[52:53]
	v_pk_fma_f32 v[22:23], v[22:23], v[78:79], v[50:51]
	v_lshl_add_u64 v[58:59], v[228:229], 0, v[120:121]
	v_lshlrev_b64 v[54:55], 1, v[58:59]
	v_pk_fma_f32 v[20:21], v[20:21], v[76:77], v[56:57]
	v_cvt_pk_bf16_f32 v50, v22, v23
	v_cvt_pk_bf16_f32 v51, v24, v25
	v_lshl_add_u64 v[56:57], s[12:13], 0, v[54:55]
	v_cvt_pk_bf16_f32 v52, v18, v19
	v_cvt_pk_bf16_f32 v53, v20, v21
	v_lshl_add_u64 v[54:55], s[18:19], 0, v[54:55]
	v_pk_mul_f32 v[56:57], v[68:69], v[20:21]
	v_pk_mul_f32 v[50:51], v[70:71], v[22:23]
	v_pk_mul_f32 v[52:53], v[72:73], v[24:25]
	v_cvt_pk_bf16_f32 v50, v50, v51
	v_pk_mul_f32 v[58:59], v[66:67], v[18:19]
	v_cvt_pk_bf16_f32 v51, v52, v53
	v_pk_fma_f32 v[10:11], v[10:11], v[74:75], v[46:47]
	v_cvt_pk_bf16_f32 v52, v58, v59
	v_cvt_pk_bf16_f32 v53, v56, v57
	flat_store_dwordx4 v[54:55], v[50:53] nt
	v_pk_fma_f32 v[16:17], v[16:17], v[80:81], v[44:45]
	v_pk_fma_f32 v[14:15], v[14:15], v[78:79], v[42:43]
	v_lshl_add_u64 v[50:51], v[230:231], 0, v[120:121]
	v_lshlrev_b64 v[46:47], 1, v[50:51]
	v_pk_fma_f32 v[12:13], v[12:13], v[76:77], v[48:49]
	v_cvt_pk_bf16_f32 v42, v14, v15
	v_cvt_pk_bf16_f32 v43, v16, v17
	v_lshl_add_u64 v[48:49], s[12:13], 0, v[46:47]
	v_cvt_pk_bf16_f32 v44, v10, v11
	v_cvt_pk_bf16_f32 v45, v12, v13
	v_lshl_add_u64 v[46:47], s[18:19], 0, v[46:47]
	v_pk_mul_f32 v[48:49], v[68:69], v[12:13]
	v_pk_mul_f32 v[42:43], v[70:71], v[14:15]
	v_pk_mul_f32 v[44:45], v[72:73], v[16:17]
	v_cvt_pk_bf16_f32 v42, v42, v43
	v_pk_mul_f32 v[50:51], v[66:67], v[10:11]
	v_cvt_pk_bf16_f32 v43, v44, v45
	v_pk_fma_f32 v[2:3], v[2:3], v[74:75], v[38:39]
	v_cvt_pk_bf16_f32 v44, v50, v51
	v_cvt_pk_bf16_f32 v45, v48, v49
	flat_store_dwordx4 v[46:47], v[42:45] nt
	v_pk_fma_f32 v[8:9], v[8:9], v[80:81], v[36:37]
	v_pk_fma_f32 v[6:7], v[6:7], v[78:79], v[34:35]
	v_lshl_add_u64 v[42:43], v[128:129], 0, v[120:121]
	v_lshlrev_b64 v[38:39], 1, v[42:43]
	v_pk_fma_f32 v[4:5], v[4:5], v[76:77], v[40:41]
	v_cvt_pk_bf16_f32 v34, v6, v7
	v_cvt_pk_bf16_f32 v35, v8, v9
	v_cvt_pk_bf16_f32 v36, v2, v3
	v_lshl_add_u64 v[40:41], s[12:13], 0, v[38:39]
	v_cvt_pk_bf16_f32 v37, v4, v5
	v_pk_mul_f32 v[42:43], v[66:67], v[2:3]
	v_lshl_add_u64 v[38:39], s[18:19], 0, v[38:39]
	v_pk_mul_f32 v[36:37], v[72:73], v[8:9]
	v_pk_mul_f32 v[34:35], v[70:71], v[6:7]
	v_pk_mul_f32 v[40:41], v[68:69], v[4:5]
	v_cvt_pk_bf16_f32 v34, v34, v35
	v_cvt_pk_bf16_f32 v35, v36, v37
	v_cvt_pk_bf16_f32 v36, v42, v43
	ds_swizzle_b32 v42, v96 offset:swizzle(SWAP,16)
	v_cvt_pk_bf16_f32 v37, v40, v41
	flat_store_dwordx4 v[38:39], v[34:37] nt
	v_cmp_eq_u32_e32 vcc, 0, v245
	s_waitcnt lgkmcnt(0)
	v_add_f32_e32 v36, v96, v42
	v_mov_b32_e32 v37, v36
	s_nop 1
	v_permlane32_swap_b32_e32 v36, v37
	v_lshl_add_u64 v[34:35], v[178:179], 3, s[20:21]
	s_and_saveexec_b64 s[30:31], vcc
	s_cbranch_execz .LBB0_1075
	v_add_f32_e32 v36, v36, v37
	v_mul_f32_e32 v36, 0x49800000, v36
	v_trunc_f32_e32 v36, v36
	v_mul_f32_e64 v37, |v36|, s78
	v_floor_f32_e32 v37, v37
	v_fma_f32 v38, v37, s74, |v36|
	v_cvt_u32_f32_e32 v38, v38
	v_cvt_u32_f32_e32 v37, v37
	v_ashrrev_i32_e32 v39, 31, v36
	v_xor_b32_e32 v36, v38, v39
	v_xor_b32_e32 v37, v37, v39
	v_sub_co_u32_e64 v36, s[8:9], v36, v39
	s_nop 1
	v_subb_co_u32_e64 v37, s[8:9], v37, v39, s[8:9]
	global_atomic_add_x2 v[34:35], v[36:37], off

.LBB0_1240:
	s_lshl_b32 s1, s1, 8
	s_add_i32 s1, s1, s72
	v_and_or_b32 v166, v156, 15, s1
	v_ashrrev_i32_e32 v177, 31, v176
	v_ashrrev_i32_e32 v167, 31, v166
	v_lshl_add_u64 v[170:171], v[176:177], 1, s[12:13]
	v_lshlrev_b64 v[188:189], 12, v[166:167]
	v_lshl_add_u64 v[186:187], v[170:171], 0, v[188:189]
	v_or_b32_e32 v198, 16, v166
	v_or_b32_e32 v200, 32, v166
	v_or_b32_e32 v174, 48, v166
	v_lshl_add_u64 v[246:247], v[186:187], 0, s[98:99]
	flat_load_dwordx4 v[182:185], v[246:247]
	v_ashrrev_i32_e32 v199, 31, v198
	v_ashrrev_i32_e32 v201, 31, v200
	v_ashrrev_i32_e32 v175, 31, v174
	v_lshlrev_b64 v[190:191], 12, v[198:199]
	v_lshlrev_b64 v[192:193], 12, v[200:201]
	v_lshlrev_b64 v[194:195], 12, v[174:175]
	v_lshl_add_u64 v[204:205], v[170:171], 0, v[190:191]
	v_lshl_add_u64 v[202:203], v[170:171], 0, v[192:193]
	v_lshl_add_u64 v[172:173], v[170:171], 0, v[194:195]
	v_lshl_add_u64 v[246:247], v[204:205], 0, s[98:99]
	flat_load_dwordx4 v[162:165], v[246:247]
	v_lshl_add_u64 v[246:247], v[202:203], 0, s[98:99]
	flat_load_dwordx4 v[158:161], v[246:247]
	v_lshl_add_u64 v[246:247], v[172:173], 0, s[98:99]
	flat_load_dwordx4 v[154:157], v[246:247]
	v_lshlrev_b64 v[196:197], 11, v[166:167]
	v_lshl_add_u64 v[206:207], v[196:197], 0, v[176:177]
	s_andn2_b64 vcc, exec, s[10:11]
	s_waitcnt vmcnt(0) lgkmcnt(0)
	v_rcp_f32_e32 v232, v232
	v_rcp_f32_e32 v233, v233
	v_rcp_f32_e32 v234, v234
	v_rcp_f32_e32 v235, v235
	v_rcp_f32_e32 v240, v240
	v_rcp_f32_e32 v241, v241
	v_rcp_f32_e32 v242, v242
	v_rcp_f32_e32 v243, v243
	s_nop 0
	v_lshlrev_b32_e32 v168, 16, v182
	v_and_b32_e32 v169, 0xffff0000, v182
	v_lshlrev_b32_e32 v208, 16, v184
	v_and_b32_e32 v209, 0xffff0000, v184
	v_lshlrev_b32_e32 v184, 16, v185
	v_and_b32_e32 v185, 0xffff0000, v185
	v_lshlrev_b32_e32 v182, 16, v183
	v_and_b32_e32 v183, 0xffff0000, v183
	v_pk_mul_f32 v[168:169], v[168:169], v[232:233]
	v_pk_fma_f32 v[168:169], v[150:151], v[110:111], v[168:169]
	v_pk_mul_f32 v[208:209], v[208:209], v[240:241]
	v_pk_fma_f32 v[150:151], v[146:147], v[106:107], v[208:209]
	v_pk_mul_f32 v[184:185], v[184:185], v[242:243]
	v_pk_fma_f32 v[146:147], v[148:149], v[108:109], v[184:185]
	v_cndmask_b32_e64 v148, 0, 1, s[10:11]
	v_pk_mul_f32 v[182:183], v[182:183], v[234:235]
	v_pk_fma_f32 v[152:153], v[152:153], v[112:113], v[182:183]
	v_cmp_ne_u32_e64 s[8:9], 1, v148
	v_cvt_pk_bf16_f32 v182, v168, v169
	v_cvt_pk_bf16_f32 v183, v152, v153
	v_cvt_pk_bf16_f32 v184, v150, v151
	v_cvt_pk_bf16_f32 v185, v146, v147
	s_cbranch_vccz .Lxs2_1
	flat_store_dwordx4 v[186:187], v[182:185] nt
.Lxs2_1:
	s_cbranch_vccnz .LBB0_1242
	v_pk_mul_f32 v[148:149], v[100:101], v[152:153]
	v_pk_mul_f32 v[182:183], v[98:99], v[168:169]
	v_pk_mul_f32 v[184:185], v[94:95], v[150:151]
	v_cvt_pk_bf16_f32 v182, v182, v183
	v_cvt_pk_bf16_f32 v183, v148, v149
	v_lshl_add_u64 v[148:149], v[206:207], 1, s[18:19]
	v_pk_mul_f32 v[186:187], v[96:97], v[146:147]
	v_cvt_pk_bf16_f32 v184, v184, v185
	s_nop 0
	v_cvt_pk_bf16_f32 v185, v186, v187
	flat_store_dwordx4 v[148:149], v[182:185] nt
.LBB0_1242:
	s_and_b64 vcc, exec, s[6:7]
	s_cbranch_vccnz .LBB0_1244
	v_pk_mul_f32 v[148:149], v[92:93], v[152:153]
	v_pk_mul_f32 v[182:183], v[90:91], v[168:169]
	v_pk_mul_f32 v[184:185], v[102:103], v[150:151]
	v_cvt_pk_bf16_f32 v182, v182, v183
	v_cvt_pk_bf16_f32 v183, v148, v149
	v_lshl_add_u64 v[148:149], v[206:207], 1, s[22:23]
	v_pk_mul_f32 v[186:187], v[104:105], v[146:147]
	v_cvt_pk_bf16_f32 v184, v184, v185
	s_nop 0
	v_cvt_pk_bf16_f32 v185, v186, v187
	flat_store_dwordx4 v[148:149], v[182:185] nt
.LBB0_1244:
	s_nop 1
	v_lshlrev_b32_e32 v182, 16, v162
	v_and_b32_e32 v183, 0xffff0000, v162
	v_lshlrev_b32_e32 v162, 16, v163
	v_and_b32_e32 v163, 0xffff0000, v163
	v_lshlrev_b32_e32 v184, 16, v164
	v_and_b32_e32 v185, 0xffff0000, v164
	v_lshlrev_b32_e32 v164, 16, v165
	v_and_b32_e32 v165, 0xffff0000, v165
	v_lshlrev_b64 v[198:199], 11, v[198:199]
	v_lshl_add_u64 v[148:149], v[198:199], 0, v[176:177]
	v_pk_mul_f32 v[162:163], v[162:163], v[234:235]
	v_pk_fma_f32 v[144:145], v[144:145], v[112:113], v[162:163]
	v_pk_mul_f32 v[182:183], v[182:183], v[232:233]
	v_pk_fma_f32 v[142:143], v[142:143], v[110:111], v[182:183]
	v_pk_mul_f32 v[184:185], v[184:185], v[240:241]
	v_pk_fma_f32 v[138:139], v[138:139], v[106:107], v[184:185]
	v_pk_mul_f32 v[164:165], v[164:165], v[242:243]
	v_pk_fma_f32 v[140:141], v[140:141], v[108:109], v[164:165]
	s_and_b64 vcc, exec, s[8:9]
	v_cvt_pk_bf16_f32 v162, v142, v143
	v_cvt_pk_bf16_f32 v163, v144, v145
	v_cvt_pk_bf16_f32 v164, v138, v139
	v_cvt_pk_bf16_f32 v165, v140, v141
	s_cbranch_vccz .Lxs2_2
	flat_store_dwordx4 v[204:205], v[162:165] nt
.Lxs2_2:
	s_cbranch_vccnz .LBB0_1246
	s_nop 0
	v_pk_mul_f32 v[164:165], v[100:101], v[144:145]
	v_pk_mul_f32 v[162:163], v[98:99], v[142:143]
	v_pk_mul_f32 v[182:183], v[96:97], v[140:141]
	v_pk_mul_f32 v[184:185], v[94:95], v[138:139]
	v_cvt_pk_bf16_f32 v162, v162, v163
	v_cvt_pk_bf16_f32 v163, v164, v165
	s_nop 0
	v_cvt_pk_bf16_f32 v164, v184, v185
	v_cvt_pk_bf16_f32 v165, v182, v183
	v_lshl_add_u64 v[182:183], v[148:149], 1, s[18:19]
	flat_store_dwordx4 v[182:183], v[162:165] nt
.LBB0_1246:
	s_and_b64 vcc, exec, s[6:7]
	s_cbranch_vccnz .LBB0_1248
	v_pk_mul_f32 v[164:165], v[92:93], v[144:145]
	v_pk_mul_f32 v[162:163], v[90:91], v[142:143]
	v_lshl_add_u64 v[148:149], v[148:149], 1, s[22:23]
	v_pk_mul_f32 v[182:183], v[104:105], v[140:141]
	v_pk_mul_f32 v[184:185], v[102:103], v[138:139]
	v_cvt_pk_bf16_f32 v162, v162, v163
	v_cvt_pk_bf16_f32 v163, v164, v165
	s_nop 0
	v_cvt_pk_bf16_f32 v164, v184, v185
	v_cvt_pk_bf16_f32 v165, v182, v183
	flat_store_dwordx4 v[148:149], v[162:165] nt
.LBB0_1248:
	v_lshlrev_b32_e32 v148, 16, v158
	v_and_b32_e32 v149, 0xffff0000, v158
	v_lshlrev_b32_e32 v158, 16, v159
	v_and_b32_e32 v159, 0xffff0000, v159
	v_lshlrev_b32_e32 v162, 16, v160
	v_and_b32_e32 v163, 0xffff0000, v160
	v_lshlrev_b32_e32 v164, 16, v161
	v_and_b32_e32 v165, 0xffff0000, v161
	v_lshlrev_b64 v[200:201], 11, v[200:201]
	v_lshl_add_u64 v[160:161], v[200:201], 0, v[176:177]
	v_pk_mul_f32 v[158:159], v[158:159], v[234:235]
	v_pk_fma_f32 v[136:137], v[136:137], v[112:113], v[158:159]
	v_pk_mul_f32 v[148:149], v[148:149], v[232:233]
	v_pk_fma_f32 v[134:135], v[134:135], v[110:111], v[148:149]
	v_pk_mul_f32 v[162:163], v[162:163], v[240:241]
	v_pk_fma_f32 v[148:149], v[130:131], v[106:107], v[162:163]
	v_pk_mul_f32 v[164:165], v[164:165], v[242:243]
	v_pk_fma_f32 v[158:159], v[132:133], v[108:109], v[164:165]
	s_and_b64 vcc, exec, s[8:9]
	v_cvt_pk_bf16_f32 v130, v134, v135
	v_cvt_pk_bf16_f32 v131, v136, v137
	v_cvt_pk_bf16_f32 v132, v148, v149
	v_cvt_pk_bf16_f32 v133, v158, v159
	s_cbranch_vccz .Lxs2_3
	flat_store_dwordx4 v[202:203], v[130:133] nt
.Lxs2_3:
	s_cbranch_vccnz .LBB0_1250
	s_nop 0
	v_pk_mul_f32 v[132:133], v[100:101], v[136:137]
	v_pk_mul_f32 v[130:131], v[98:99], v[134:135]
	v_pk_mul_f32 v[162:163], v[96:97], v[158:159]
	v_pk_mul_f32 v[164:165], v[94:95], v[148:149]
	v_cvt_pk_bf16_f32 v130, v130, v131
	v_cvt_pk_bf16_f32 v131, v132, v133
	s_nop 0
	v_cvt_pk_bf16_f32 v132, v164, v165
	v_cvt_pk_bf16_f32 v133, v162, v163
	v_lshl_add_u64 v[162:163], v[160:161], 1, s[18:19]
	flat_store_dwordx4 v[162:163], v[130:133] nt
.LBB0_1250:
	s_and_b64 vcc, exec, s[6:7]
	s_cbranch_vccnz .LBB0_1252
	v_pk_mul_f32 v[132:133], v[92:93], v[136:137]
	v_pk_mul_f32 v[130:131], v[90:91], v[134:135]
	v_lshl_add_u64 v[160:161], v[160:161], 1, s[22:23]
	v_pk_mul_f32 v[162:163], v[104:105], v[158:159]
	v_pk_mul_f32 v[164:165], v[102:103], v[148:149]
	v_cvt_pk_bf16_f32 v130, v130, v131
	v_cvt_pk_bf16_f32 v131, v132, v133
	s_nop 0
	v_cvt_pk_bf16_f32 v132, v164, v165
	v_cvt_pk_bf16_f32 v133, v162, v163
	flat_store_dwordx4 v[160:161], v[130:133] nt
.LBB0_1252:
	s_nop 1
	v_lshlrev_b32_e32 v132, 16, v154
	v_and_b32_e32 v133, 0xffff0000, v154
	v_lshlrev_b32_e32 v154, 16, v155
	v_and_b32_e32 v155, 0xffff0000, v155
	v_lshlrev_b32_e32 v160, 16, v156
	v_and_b32_e32 v161, 0xffff0000, v156
	v_lshlrev_b32_e32 v162, 16, v157
	v_and_b32_e32 v163, 0xffff0000, v157
	v_lshlrev_b64 v[202:203], 11, v[174:175]
	v_lshl_add_u64 v[130:131], v[202:203], 0, v[176:177]
	v_pk_mul_f32 v[154:155], v[154:155], v[234:235]
	v_pk_fma_f32 v[154:155], v[128:129], v[112:113], v[154:155]
	v_pk_mul_f32 v[132:133], v[132:133], v[232:233]
	v_pk_fma_f32 v[156:157], v[126:127], v[110:111], v[132:133]
	v_pk_mul_f32 v[160:161], v[160:161], v[240:241]
	v_pk_fma_f32 v[160:161], v[122:123], v[106:107], v[160:161]
	v_pk_mul_f32 v[162:163], v[162:163], v[242:243]
	v_pk_fma_f32 v[162:163], v[124:125], v[108:109], v[162:163]
	s_and_b64 vcc, exec, s[8:9]
	v_cvt_pk_bf16_f32 v122, v156, v157
	v_cvt_pk_bf16_f32 v123, v154, v155
	v_cvt_pk_bf16_f32 v124, v160, v161
	v_cvt_pk_bf16_f32 v125, v162, v163
	s_cbranch_vccz .Lxs2_4
	flat_store_dwordx4 v[172:173], v[122:125] nt
.Lxs2_4:
	s_cbranch_vccnz .LBB0_1254
	s_nop 0
	v_pk_mul_f32 v[124:125], v[100:101], v[154:155]
	v_pk_mul_f32 v[122:123], v[98:99], v[156:157]
	v_pk_mul_f32 v[126:127], v[96:97], v[162:163]
	v_pk_mul_f32 v[128:129], v[94:95], v[160:161]
	v_cvt_pk_bf16_f32 v122, v122, v123
	v_cvt_pk_bf16_f32 v123, v124, v125
	s_nop 0
	v_cvt_pk_bf16_f32 v124, v128, v129
	v_cvt_pk_bf16_f32 v125, v126, v127
	v_lshl_add_u64 v[126:127], v[130:131], 1, s[18:19]
	flat_store_dwordx4 v[126:127], v[122:125] nt
.LBB0_1254:
	s_and_b64 vcc, exec, s[6:7]
	s_cbranch_vccnz .LBB0_1256
	v_pk_mul_f32 v[124:125], v[92:93], v[154:155]
	v_pk_mul_f32 v[122:123], v[90:91], v[156:157]
	v_pk_mul_f32 v[126:127], v[104:105], v[162:163]
	v_pk_mul_f32 v[128:129], v[102:103], v[160:161]
	v_cvt_pk_bf16_f32 v122, v122, v123
	v_cvt_pk_bf16_f32 v123, v124, v125
	s_nop 0
	v_cvt_pk_bf16_f32 v124, v128, v129
	v_cvt_pk_bf16_f32 v125, v126, v127
	v_lshl_add_u64 v[126:127], v[130:131], 1, s[22:23]
	flat_store_dwordx4 v[126:127], v[122:125] nt
.LBB0_1256:
	v_add_u32_e32 v186, 0x80, v166
	v_ashrrev_i32_e32 v187, 31, v186
	v_lshlrev_b64 v[204:205], 12, v[186:187]
	v_add_u32_e32 v164, 0x90, v166
	v_add_u32_e32 v172, 0xa0, v166
	v_add_u32_e32 v220, 0xb0, v166
	v_lshl_add_u64 v[214:215], v[170:171], 0, v[204:205]
	v_ashrrev_i32_e32 v165, 31, v164
	v_ashrrev_i32_e32 v173, 31, v172
	v_ashrrev_i32_e32 v221, 31, v220
	v_lshl_add_u64 v[246:247], v[214:215], 0, s[98:99]
	flat_load_dwordx4 v[182:185], v[246:247]
	v_lshlrev_b64 v[206:207], 12, v[164:165]
	v_lshlrev_b64 v[208:209], 12, v[172:173]
	v_lshlrev_b64 v[210:211], 12, v[220:221]
	v_lshl_add_u64 v[174:175], v[170:171], 0, v[206:207]
	v_lshl_add_u64 v[222:223], v[170:171], 0, v[208:209]
	v_lshl_add_u64 v[218:219], v[170:171], 0, v[210:211]
	v_lshl_add_u64 v[246:247], v[174:175], 0, s[98:99]
	flat_load_dwordx4 v[130:133], v[246:247]
	v_lshl_add_u64 v[246:247], v[222:223], 0, s[98:99]
	flat_load_dwordx4 v[126:129], v[246:247]
	v_lshl_add_u64 v[246:247], v[218:219], 0, s[98:99]
	flat_load_dwordx4 v[122:125], v[246:247]
	v_lshlrev_b64 v[212:213], 11, v[186:187]
	v_lshl_add_u64 v[170:171], v[212:213], 0, v[176:177]
	s_and_b64 vcc, exec, s[8:9]
	s_waitcnt vmcnt(0) lgkmcnt(0)
	v_lshlrev_b32_e32 v216, 16, v182
	v_and_b32_e32 v217, 0xffff0000, v182
	v_lshlrev_b32_e32 v182, 16, v183
	v_and_b32_e32 v183, 0xffff0000, v183
	v_lshlrev_b32_e32 v230, 16, v184
	v_and_b32_e32 v231, 0xffff0000, v184
	v_lshlrev_b32_e32 v184, 16, v185
	v_and_b32_e32 v185, 0xffff0000, v185
	v_pk_mul_f32 v[182:183], v[182:183], v[234:235]
	v_pk_fma_f32 v[120:121], v[120:121], v[112:113], v[182:183]
	v_pk_mul_f32 v[216:217], v[216:217], v[232:233]
	v_pk_fma_f32 v[118:119], v[118:119], v[110:111], v[216:217]
	v_pk_mul_f32 v[230:231], v[230:231], v[240:241]
	v_pk_fma_f32 v[114:115], v[114:115], v[106:107], v[230:231]
	v_pk_mul_f32 v[184:185], v[184:185], v[242:243]
	v_pk_fma_f32 v[116:117], v[116:117], v[108:109], v[184:185]
	v_cvt_pk_bf16_f32 v182, v118, v119
	v_cvt_pk_bf16_f32 v183, v120, v121
	v_cvt_pk_bf16_f32 v184, v114, v115
	s_nop 0
	v_cvt_pk_bf16_f32 v185, v116, v117
	s_cbranch_vccz .Lxs2_5
	flat_store_dwordx4 v[214:215], v[182:185] nt
.Lxs2_5:
	s_cbranch_vccnz .LBB0_1258
	s_nop 0
	v_pk_mul_f32 v[184:185], v[100:101], v[120:121]
	v_pk_mul_f32 v[182:183], v[98:99], v[118:119]
	v_pk_mul_f32 v[186:187], v[96:97], v[116:117]
	v_pk_mul_f32 v[214:215], v[94:95], v[114:115]
	v_cvt_pk_bf16_f32 v182, v182, v183
	v_cvt_pk_bf16_f32 v183, v184, v185
	s_nop 0
	v_cvt_pk_bf16_f32 v184, v214, v215
	v_cvt_pk_bf16_f32 v185, v186, v187
	v_lshl_add_u64 v[186:187], v[170:171], 1, s[18:19]
	flat_store_dwordx4 v[186:187], v[182:185] nt
.LBB0_1258:
	s_and_b64 vcc, exec, s[6:7]
	s_cbranch_vccnz .LBB0_1260
	v_pk_mul_f32 v[184:185], v[92:93], v[120:121]
	v_pk_mul_f32 v[182:183], v[90:91], v[118:119]
	v_lshl_add_u64 v[170:171], v[170:171], 1, s[22:23]
	v_pk_mul_f32 v[186:187], v[104:105], v[116:117]
	v_pk_mul_f32 v[214:215], v[102:103], v[114:115]
	v_cvt_pk_bf16_f32 v182, v182, v183
	v_cvt_pk_bf16_f32 v183, v184, v185
	s_nop 0
	v_cvt_pk_bf16_f32 v184, v214, v215
	v_cvt_pk_bf16_f32 v185, v186, v187
	flat_store_dwordx4 v[170:171], v[182:185] nt
.LBB0_1260:
	v_lshlrev_b32_e32 v170, 16, v130
	v_and_b32_e32 v171, 0xffff0000, v130
	v_lshlrev_b32_e32 v130, 16, v131
	v_and_b32_e32 v131, 0xffff0000, v131
	v_lshlrev_b32_e32 v182, 16, v132
	v_and_b32_e32 v183, 0xffff0000, v132
	v_lshlrev_b32_e32 v184, 16, v133
	v_and_b32_e32 v185, 0xffff0000, v133
	v_lshlrev_b64 v[214:215], 11, v[164:165]
	v_lshl_add_u64 v[216:217], v[214:215], 0, v[176:177]
	v_pk_mul_f32 v[130:131], v[130:131], v[234:235]
	v_pk_fma_f32 v[130:131], v[88:89], v[112:113], v[130:131]
	v_pk_mul_f32 v[170:171], v[170:171], v[232:233]
	v_pk_fma_f32 v[132:133], v[86:87], v[110:111], v[170:171]
	v_pk_mul_f32 v[182:183], v[182:183], v[240:241]
	v_pk_fma_f32 v[164:165], v[82:83], v[106:107], v[182:183]
	v_pk_mul_f32 v[184:185], v[184:185], v[242:243]
	v_pk_fma_f32 v[170:171], v[84:85], v[108:109], v[184:185]
	s_and_b64 vcc, exec, s[8:9]
	v_cvt_pk_bf16_f32 v82, v132, v133
	v_cvt_pk_bf16_f32 v83, v130, v131
	v_cvt_pk_bf16_f32 v84, v164, v165
	v_cvt_pk_bf16_f32 v85, v170, v171
	s_cbranch_vccz .Lxs2_6
	flat_store_dwordx4 v[174:175], v[82:85] nt
.Lxs2_6:
	s_cbranch_vccnz .LBB0_1262
	s_nop 0
	v_pk_mul_f32 v[84:85], v[100:101], v[130:131]
	v_pk_mul_f32 v[82:83], v[98:99], v[132:133]
	v_pk_mul_f32 v[86:87], v[96:97], v[170:171]
	v_pk_mul_f32 v[88:89], v[94:95], v[164:165]
	v_cvt_pk_bf16_f32 v82, v82, v83
	v_cvt_pk_bf16_f32 v83, v84, v85
	s_nop 0
	v_cvt_pk_bf16_f32 v84, v88, v89
	v_cvt_pk_bf16_f32 v85, v86, v87
	v_lshl_add_u64 v[86:87], v[216:217], 1, s[18:19]
	flat_store_dwordx4 v[86:87], v[82:85] nt
.LBB0_1262:
	s_and_b64 vcc, exec, s[6:7]
	s_cbranch_vccnz .LBB0_1264
	v_pk_mul_f32 v[84:85], v[92:93], v[130:131]
	v_pk_mul_f32 v[82:83], v[90:91], v[132:133]
	v_pk_mul_f32 v[86:87], v[104:105], v[170:171]
	v_pk_mul_f32 v[88:89], v[102:103], v[164:165]
	v_cvt_pk_bf16_f32 v82, v82, v83
	v_cvt_pk_bf16_f32 v83, v84, v85
	s_nop 0
	v_cvt_pk_bf16_f32 v84, v88, v89
	v_cvt_pk_bf16_f32 v85, v86, v87
	v_lshl_add_u64 v[86:87], v[216:217], 1, s[22:23]
	flat_store_dwordx4 v[86:87], v[82:85] nt
.LBB0_1264:
	s_nop 1
	v_lshlrev_b32_e32 v84, 16, v126
	v_and_b32_e32 v85, 0xffff0000, v126
	v_lshlrev_b32_e32 v86, 16, v127
	v_and_b32_e32 v87, 0xffff0000, v127
	v_lshlrev_b32_e32 v88, 16, v128
	v_and_b32_e32 v89, 0xffff0000, v128
	v_lshlrev_b32_e32 v174, 16, v129
	v_and_b32_e32 v175, 0xffff0000, v129
	v_lshlrev_b64 v[216:217], 11, v[172:173]
	v_lshl_add_u64 v[82:83], v[216:217], 0, v[176:177]
	v_pk_mul_f32 v[86:87], v[86:87], v[234:235]
	v_pk_fma_f32 v[126:127], v[80:81], v[112:113], v[86:87]
	v_pk_mul_f32 v[84:85], v[84:85], v[232:233]
	v_pk_fma_f32 v[128:129], v[78:79], v[110:111], v[84:85]
	v_pk_mul_f32 v[88:89], v[88:89], v[240:241]
	v_pk_fma_f32 v[172:173], v[74:75], v[106:107], v[88:89]
	v_pk_mul_f32 v[174:175], v[174:175], v[242:243]
	v_pk_fma_f32 v[174:175], v[76:77], v[108:109], v[174:175]
	s_and_b64 vcc, exec, s[8:9]
	v_cvt_pk_bf16_f32 v74, v128, v129
	v_cvt_pk_bf16_f32 v75, v126, v127
	v_cvt_pk_bf16_f32 v76, v172, v173
	v_cvt_pk_bf16_f32 v77, v174, v175
	s_cbranch_vccz .Lxs2_7
	flat_store_dwordx4 v[222:223], v[74:77] nt
.Lxs2_7:
	s_cbranch_vccnz .LBB0_1266
	s_nop 0
	v_pk_mul_f32 v[76:77], v[100:101], v[126:127]
	v_pk_mul_f32 v[74:75], v[98:99], v[128:129]
	v_pk_mul_f32 v[78:79], v[96:97], v[174:175]
	v_pk_mul_f32 v[80:81], v[94:95], v[172:173]
	v_cvt_pk_bf16_f32 v74, v74, v75
	v_cvt_pk_bf16_f32 v75, v76, v77
	s_nop 0
	v_cvt_pk_bf16_f32 v76, v80, v81
	v_cvt_pk_bf16_f32 v77, v78, v79
	v_lshl_add_u64 v[78:79], v[82:83], 1, s[18:19]
	flat_store_dwordx4 v[78:79], v[74:77] nt
.LBB0_1266:
	s_and_b64 vcc, exec, s[6:7]
	s_cbranch_vccnz .LBB0_1268
	v_pk_mul_f32 v[76:77], v[92:93], v[126:127]
	v_pk_mul_f32 v[74:75], v[90:91], v[128:129]
	v_pk_mul_f32 v[78:79], v[104:105], v[174:175]
	v_pk_mul_f32 v[80:81], v[102:103], v[172:173]
	v_cvt_pk_bf16_f32 v74, v74, v75
	v_cvt_pk_bf16_f32 v75, v76, v77
	s_nop 0
	v_cvt_pk_bf16_f32 v76, v80, v81
	v_cvt_pk_bf16_f32 v77, v78, v79
	v_lshl_add_u64 v[78:79], v[82:83], 1, s[22:23]
	flat_store_dwordx4 v[78:79], v[74:77] nt
.LBB0_1268:
	s_nop 1
	v_lshlrev_b32_e32 v76, 16, v122
	v_and_b32_e32 v77, 0xffff0000, v122
	v_lshlrev_b32_e32 v78, 16, v123
	v_and_b32_e32 v79, 0xffff0000, v123
	v_lshlrev_b32_e32 v80, 16, v124
	v_and_b32_e32 v81, 0xffff0000, v124
	v_lshlrev_b32_e32 v82, 16, v125
	v_and_b32_e32 v83, 0xffff0000, v125
	v_lshlrev_b64 v[122:123], 11, v[220:221]
	v_lshl_add_u64 v[74:75], v[122:123], 0, v[176:177]
	v_pk_mul_f32 v[78:79], v[78:79], v[234:235]
	v_pk_fma_f32 v[112:113], v[72:73], v[112:113], v[78:79]
	v_pk_mul_f32 v[76:77], v[76:77], v[232:233]
	v_pk_fma_f32 v[110:111], v[70:71], v[110:111], v[76:77]
	v_pk_mul_f32 v[80:81], v[80:81], v[240:241]
	v_pk_fma_f32 v[106:107], v[66:67], v[106:107], v[80:81]
	v_pk_mul_f32 v[82:83], v[82:83], v[242:243]
	v_pk_fma_f32 v[108:109], v[68:69], v[108:109], v[82:83]
	s_and_b64 vcc, exec, s[8:9]
	v_cvt_pk_bf16_f32 v66, v110, v111
	v_cvt_pk_bf16_f32 v67, v112, v113
	v_cvt_pk_bf16_f32 v68, v106, v107
	v_cvt_pk_bf16_f32 v69, v108, v109
	s_cbranch_vccz .Lxs2_8
	flat_store_dwordx4 v[218:219], v[66:69] nt
.Lxs2_8:
	s_cbranch_vccnz .LBB0_1270
	s_nop 0
	v_pk_mul_f32 v[68:69], v[100:101], v[112:113]
	v_pk_mul_f32 v[66:67], v[98:99], v[110:111]
	v_pk_mul_f32 v[70:71], v[96:97], v[108:109]
	v_pk_mul_f32 v[72:73], v[94:95], v[106:107]
	v_cvt_pk_bf16_f32 v66, v66, v67
	v_cvt_pk_bf16_f32 v67, v68, v69
	s_nop 0
	v_cvt_pk_bf16_f32 v68, v72, v73
	v_cvt_pk_bf16_f32 v69, v70, v71
	v_lshl_add_u64 v[70:71], v[74:75], 1, s[18:19]
	flat_store_dwordx4 v[70:71], v[66:69] nt
.LBB0_1270:
	s_and_b64 vcc, exec, s[6:7]
	s_cbranch_vccnz .LBB0_1272
	v_pk_mul_f32 v[68:69], v[92:93], v[112:113]
	v_pk_mul_f32 v[66:67], v[90:91], v[110:111]
	v_pk_mul_f32 v[70:71], v[104:105], v[108:109]
	v_pk_mul_f32 v[72:73], v[102:103], v[106:107]
	v_cvt_pk_bf16_f32 v66, v66, v67
	v_cvt_pk_bf16_f32 v67, v68, v69
	s_nop 0
	v_cvt_pk_bf16_f32 v68, v72, v73
	v_cvt_pk_bf16_f32 v69, v70, v71
	v_lshl_add_u64 v[70:71], v[74:75], 1, s[22:23]
	flat_store_dwordx4 v[70:71], v[66:69] nt

.LBB0_1276:
	v_ashrrev_i32_e32 v103, 31, v102
	v_lshl_add_u64 v[90:91], s[12:13], 0, v[188:189]
	v_lshlrev_b64 v[104:105], 1, v[102:103]
	v_lshl_add_u64 v[186:187], v[90:91], 0, v[104:105]
	v_lshl_add_u64 v[90:91], s[12:13], 0, v[190:191]
	v_lshl_add_u64 v[246:247], v[186:187], 0, s[98:99]
	flat_load_dwordx4 v[182:185], v[246:247]
	v_lshl_add_u64 v[92:93], s[12:13], 0, v[192:193]
	v_lshl_add_u64 v[94:95], s[12:13], 0, v[194:195]
	v_lshl_add_u64 v[178:179], v[90:91], 0, v[104:105]
	v_lshl_add_u64 v[176:177], v[92:93], 0, v[104:105]
	v_lshl_add_u64 v[124:125], v[94:95], 0, v[104:105]
	v_lshl_add_u64 v[246:247], v[178:179], 0, s[98:99]
	flat_load_dwordx4 v[98:101], v[246:247]
	v_lshl_add_u64 v[246:247], v[176:177], 0, s[98:99]
	flat_load_dwordx4 v[94:97], v[246:247]
	v_lshl_add_u64 v[246:247], v[124:125], 0, s[98:99]
	flat_load_dwordx4 v[90:93], v[246:247]
	v_lshl_add_u64 v[188:189], v[196:197], 0, v[102:103]
	s_and_b64 vcc, exec, s[8:9]
	s_waitcnt vmcnt(0) lgkmcnt(0)
	v_rcp_f32_e32 v232, v232
	v_rcp_f32_e32 v233, v233
	v_rcp_f32_e32 v234, v234
	v_rcp_f32_e32 v235, v235
	v_rcp_f32_e32 v240, v240
	v_rcp_f32_e32 v241, v241
	v_rcp_f32_e32 v242, v242
	v_rcp_f32_e32 v243, v243
	s_nop 0
	v_lshlrev_b32_e32 v190, 16, v182
	v_and_b32_e32 v191, 0xffff0000, v182
	v_lshlrev_b32_e32 v182, 16, v183
	v_and_b32_e32 v183, 0xffff0000, v183
	v_lshlrev_b32_e32 v192, 16, v184
	v_and_b32_e32 v193, 0xffff0000, v184
	v_lshlrev_b32_e32 v184, 16, v185
	v_and_b32_e32 v185, 0xffff0000, v185
	v_pk_mul_f32 v[182:183], v[182:183], v[234:235]
	v_pk_fma_f32 v[64:65], v[64:65], v[88:89], v[182:183]
	v_pk_mul_f32 v[190:191], v[190:191], v[232:233]
	v_pk_fma_f32 v[62:63], v[62:63], v[86:87], v[190:191]
	v_pk_mul_f32 v[192:193], v[192:193], v[240:241]
	v_pk_fma_f32 v[58:59], v[58:59], v[82:83], v[192:193]
	v_pk_mul_f32 v[184:185], v[184:185], v[242:243]
	v_pk_fma_f32 v[60:61], v[60:61], v[84:85], v[184:185]
	v_cvt_pk_bf16_f32 v182, v62, v63
	v_cvt_pk_bf16_f32 v183, v64, v65
	v_cvt_pk_bf16_f32 v184, v58, v59
	s_nop 0
	v_cvt_pk_bf16_f32 v185, v60, v61
	s_cbranch_vccz .Lxs2_9
	flat_store_dwordx4 v[186:187], v[182:185] nt
.Lxs2_9:
	s_cbranch_vccnz .LBB0_1278
	s_nop 0
	v_pk_mul_f32 v[184:185], v[76:77], v[64:65]
	v_pk_mul_f32 v[182:183], v[74:75], v[62:63]
	v_pk_mul_f32 v[186:187], v[72:73], v[60:61]
	v_pk_mul_f32 v[190:191], v[70:71], v[58:59]
	v_cvt_pk_bf16_f32 v182, v182, v183
	v_cvt_pk_bf16_f32 v183, v184, v185
	s_nop 0
	v_cvt_pk_bf16_f32 v184, v190, v191
	v_cvt_pk_bf16_f32 v185, v186, v187
	v_lshl_add_u64 v[186:187], v[188:189], 1, s[18:19]
	flat_store_dwordx4 v[186:187], v[182:185] nt
.LBB0_1278:
	s_and_b64 vcc, exec, s[6:7]
	s_cbranch_vccnz .LBB0_1280
	v_pk_mul_f32 v[184:185], v[68:69], v[64:65]
	v_pk_mul_f32 v[182:183], v[66:67], v[62:63]
	v_pk_mul_f32 v[186:187], v[80:81], v[60:61]
	v_pk_mul_f32 v[190:191], v[78:79], v[58:59]
	v_cvt_pk_bf16_f32 v182, v182, v183
	v_cvt_pk_bf16_f32 v183, v184, v185
	s_nop 0
	v_cvt_pk_bf16_f32 v184, v190, v191
	v_cvt_pk_bf16_f32 v185, v186, v187
	v_lshl_add_u64 v[186:187], v[188:189], 1, s[22:23]
	flat_store_dwordx4 v[186:187], v[182:185] nt
.LBB0_1280:
	s_nop 1
	v_lshlrev_b32_e32 v182, 16, v98
	v_and_b32_e32 v183, 0xffff0000, v98
	v_lshlrev_b32_e32 v184, 16, v99
	v_and_b32_e32 v185, 0xffff0000, v99
	v_lshlrev_b32_e32 v186, 16, v100
	v_and_b32_e32 v187, 0xffff0000, v100
	v_lshlrev_b32_e32 v100, 16, v101
	v_and_b32_e32 v101, 0xffff0000, v101
	v_lshl_add_u64 v[98:99], v[198:199], 0, v[102:103]
	v_pk_mul_f32 v[184:185], v[184:185], v[234:235]
	v_pk_fma_f32 v[56:57], v[56:57], v[88:89], v[184:185]
	v_pk_mul_f32 v[182:183], v[182:183], v[232:233]
	v_pk_fma_f32 v[54:55], v[54:55], v[86:87], v[182:183]
	v_pk_mul_f32 v[186:187], v[186:187], v[240:241]
	v_pk_fma_f32 v[50:51], v[50:51], v[82:83], v[186:187]
	v_pk_mul_f32 v[100:101], v[100:101], v[242:243]
	v_pk_fma_f32 v[52:53], v[52:53], v[84:85], v[100:101]
	s_and_b64 vcc, exec, s[8:9]
	v_cvt_pk_bf16_f32 v182, v54, v55
	v_cvt_pk_bf16_f32 v183, v56, v57
	v_cvt_pk_bf16_f32 v184, v50, v51
	v_cvt_pk_bf16_f32 v185, v52, v53
	s_cbranch_vccz .Lxs2_10
	flat_store_dwordx4 v[178:179], v[182:185] nt
.Lxs2_10:
	s_cbranch_vccnz .LBB0_1282
	v_pk_mul_f32 v[100:101], v[76:77], v[56:57]
	v_pk_mul_f32 v[178:179], v[74:75], v[54:55]
	v_pk_mul_f32 v[184:185], v[70:71], v[50:51]
	v_cvt_pk_bf16_f32 v182, v178, v179
	v_cvt_pk_bf16_f32 v183, v100, v101
	v_lshl_add_u64 v[100:101], v[98:99], 1, s[18:19]
	v_pk_mul_f32 v[186:187], v[72:73], v[52:53]
	v_cvt_pk_bf16_f32 v184, v184, v185
	s_nop 0
	v_cvt_pk_bf16_f32 v185, v186, v187
	flat_store_dwordx4 v[100:101], v[182:185] nt
.LBB0_1282:
	s_and_b64 vcc, exec, s[6:7]
	s_cbranch_vccnz .LBB0_1284
	v_pk_mul_f32 v[184:185], v[78:79], v[50:51]
	v_lshl_add_u64 v[98:99], v[98:99], 1, s[22:23]
	v_pk_mul_f32 v[100:101], v[68:69], v[56:57]
	v_pk_mul_f32 v[178:179], v[66:67], v[54:55]
	v_pk_mul_f32 v[186:187], v[80:81], v[52:53]
	v_cvt_pk_bf16_f32 v182, v178, v179
	v_cvt_pk_bf16_f32 v183, v100, v101
	v_cvt_pk_bf16_f32 v184, v184, v185
	s_nop 0
	v_cvt_pk_bf16_f32 v185, v186, v187
	flat_store_dwordx4 v[98:99], v[182:185] nt
.LBB0_1284:
	v_lshlrev_b32_e32 v100, 16, v94
	v_and_b32_e32 v101, 0xffff0000, v94
	v_lshlrev_b32_e32 v94, 16, v95
	v_and_b32_e32 v95, 0xffff0000, v95
	v_lshlrev_b32_e32 v178, 16, v96
	v_and_b32_e32 v179, 0xffff0000, v96
	v_lshlrev_b32_e32 v96, 16, v97
	v_and_b32_e32 v97, 0xffff0000, v97
	v_lshl_add_u64 v[98:99], v[200:201], 0, v[102:103]
	v_pk_mul_f32 v[94:95], v[94:95], v[234:235]
	v_pk_fma_f32 v[48:49], v[48:49], v[88:89], v[94:95]
	v_pk_mul_f32 v[100:101], v[100:101], v[232:233]
	v_pk_fma_f32 v[46:47], v[46:47], v[86:87], v[100:101]
	v_pk_mul_f32 v[178:179], v[178:179], v[240:241]
	v_pk_fma_f32 v[94:95], v[42:43], v[82:83], v[178:179]
	v_pk_mul_f32 v[96:97], v[96:97], v[242:243]
	v_pk_fma_f32 v[96:97], v[44:45], v[84:85], v[96:97]
	s_and_b64 vcc, exec, s[8:9]
	v_cvt_pk_bf16_f32 v42, v46, v47
	v_cvt_pk_bf16_f32 v43, v48, v49
	v_cvt_pk_bf16_f32 v44, v94, v95
	v_cvt_pk_bf16_f32 v45, v96, v97
	s_cbranch_vccz .Lxs2_11
	flat_store_dwordx4 v[176:177], v[42:45] nt
.Lxs2_11:
	s_cbranch_vccnz .LBB0_1286
	s_nop 0
	v_pk_mul_f32 v[44:45], v[76:77], v[48:49]
	v_pk_mul_f32 v[42:43], v[74:75], v[46:47]
	v_pk_mul_f32 v[100:101], v[72:73], v[96:97]
	v_pk_mul_f32 v[176:177], v[70:71], v[94:95]
	v_cvt_pk_bf16_f32 v42, v42, v43
	v_cvt_pk_bf16_f32 v43, v44, v45
	s_nop 0
	v_cvt_pk_bf16_f32 v44, v176, v177
	v_cvt_pk_bf16_f32 v45, v100, v101
	v_lshl_add_u64 v[100:101], v[98:99], 1, s[18:19]
	flat_store_dwordx4 v[100:101], v[42:45] nt
.LBB0_1286:
	s_and_b64 vcc, exec, s[6:7]
	s_cbranch_vccnz .LBB0_1288
	v_pk_mul_f32 v[44:45], v[68:69], v[48:49]
	v_pk_mul_f32 v[42:43], v[66:67], v[46:47]
	v_lshl_add_u64 v[98:99], v[98:99], 1, s[22:23]
	v_pk_mul_f32 v[100:101], v[80:81], v[96:97]
	v_pk_mul_f32 v[176:177], v[78:79], v[94:95]
	v_cvt_pk_bf16_f32 v42, v42, v43
	v_cvt_pk_bf16_f32 v43, v44, v45
	s_nop 0
	v_cvt_pk_bf16_f32 v44, v176, v177
	v_cvt_pk_bf16_f32 v45, v100, v101
	flat_store_dwordx4 v[98:99], v[42:45] nt
.LBB0_1288:
	s_nop 1
	v_lshlrev_b32_e32 v44, 16, v90
	v_and_b32_e32 v45, 0xffff0000, v90
	v_lshlrev_b32_e32 v90, 16, v91
	v_and_b32_e32 v91, 0xffff0000, v91
	v_lshlrev_b32_e32 v98, 16, v92
	v_and_b32_e32 v99, 0xffff0000, v92
	v_lshlrev_b32_e32 v100, 16, v93
	v_and_b32_e32 v101, 0xffff0000, v93
	v_lshl_add_u64 v[42:43], v[202:203], 0, v[102:103]
	v_pk_mul_f32 v[90:91], v[90:91], v[234:235]
	v_pk_fma_f32 v[90:91], v[40:41], v[88:89], v[90:91]
	v_pk_mul_f32 v[44:45], v[44:45], v[232:233]
	v_pk_fma_f32 v[92:93], v[38:39], v[86:87], v[44:45]
	v_pk_mul_f32 v[98:99], v[98:99], v[240:241]
	v_pk_fma_f32 v[98:99], v[34:35], v[82:83], v[98:99]
	v_pk_mul_f32 v[100:101], v[100:101], v[242:243]
	v_pk_fma_f32 v[100:101], v[36:37], v[84:85], v[100:101]
	s_and_b64 vcc, exec, s[8:9]
	v_cvt_pk_bf16_f32 v34, v92, v93
	v_cvt_pk_bf16_f32 v35, v90, v91
	v_cvt_pk_bf16_f32 v36, v98, v99
	v_cvt_pk_bf16_f32 v37, v100, v101
	s_cbranch_vccz .Lxs2_12
	flat_store_dwordx4 v[124:125], v[34:37] nt
.Lxs2_12:
	s_cbranch_vccnz .LBB0_1290
	s_nop 0
	v_pk_mul_f32 v[36:37], v[76:77], v[90:91]
	v_pk_mul_f32 v[34:35], v[74:75], v[92:93]
	v_pk_mul_f32 v[38:39], v[72:73], v[100:101]
	v_pk_mul_f32 v[40:41], v[70:71], v[98:99]
	v_cvt_pk_bf16_f32 v34, v34, v35
	v_cvt_pk_bf16_f32 v35, v36, v37
	s_nop 0
	v_cvt_pk_bf16_f32 v36, v40, v41
	v_cvt_pk_bf16_f32 v37, v38, v39
	v_lshl_add_u64 v[38:39], v[42:43], 1, s[18:19]
	flat_store_dwordx4 v[38:39], v[34:37] nt
.LBB0_1290:
	s_and_b64 vcc, exec, s[6:7]
	s_cbranch_vccnz .LBB0_1292
	v_pk_mul_f32 v[36:37], v[68:69], v[90:91]
	v_pk_mul_f32 v[34:35], v[66:67], v[92:93]
	v_pk_mul_f32 v[38:39], v[80:81], v[100:101]
	v_pk_mul_f32 v[40:41], v[78:79], v[98:99]
	v_cvt_pk_bf16_f32 v34, v34, v35
	v_cvt_pk_bf16_f32 v35, v36, v37
	s_nop 0
	v_cvt_pk_bf16_f32 v36, v40, v41
	v_cvt_pk_bf16_f32 v37, v38, v39
	v_lshl_add_u64 v[38:39], v[42:43], 1, s[22:23]
	flat_store_dwordx4 v[38:39], v[34:37] nt
.LBB0_1292:
	s_nop 1
	v_lshl_add_u64 v[34:35], s[12:13], 0, v[204:205]
	v_lshl_add_u64 v[186:187], v[34:35], 0, v[104:105]
	v_lshl_add_u64 v[34:35], s[12:13], 0, v[206:207]
	v_lshl_add_u64 v[246:247], v[186:187], 0, s[98:99]
	flat_load_dwordx4 v[182:185], v[246:247]
	v_lshl_add_u64 v[36:37], s[12:13], 0, v[208:209]
	v_lshl_add_u64 v[38:39], s[12:13], 0, v[210:211]
	v_lshl_add_u64 v[176:177], v[34:35], 0, v[104:105]
	v_lshl_add_u64 v[124:125], v[36:37], 0, v[104:105]
	v_lshl_add_u64 v[104:105], v[38:39], 0, v[104:105]
	v_lshl_add_u64 v[246:247], v[176:177], 0, s[98:99]
	flat_load_dwordx4 v[42:45], v[246:247]
	v_lshl_add_u64 v[246:247], v[124:125], 0, s[98:99]
	flat_load_dwordx4 v[38:41], v[246:247]
	v_lshl_add_u64 v[246:247], v[104:105], 0, s[98:99]
	flat_load_dwordx4 v[34:37], v[246:247]
	v_lshl_add_u64 v[178:179], v[212:213], 0, v[102:103]
	s_and_b64 vcc, exec, s[8:9]
	s_waitcnt vmcnt(0) lgkmcnt(0)
	v_lshlrev_b32_e32 v188, 16, v182
	v_and_b32_e32 v189, 0xffff0000, v182
	v_lshlrev_b32_e32 v182, 16, v183
	v_and_b32_e32 v183, 0xffff0000, v183
	v_lshlrev_b32_e32 v190, 16, v184
	v_and_b32_e32 v191, 0xffff0000, v184
	v_lshlrev_b32_e32 v184, 16, v185
	v_and_b32_e32 v185, 0xffff0000, v185
	v_pk_mul_f32 v[182:183], v[182:183], v[234:235]
	v_pk_fma_f32 v[32:33], v[32:33], v[88:89], v[182:183]
	v_pk_mul_f32 v[188:189], v[188:189], v[232:233]
	v_pk_fma_f32 v[30:31], v[30:31], v[86:87], v[188:189]
	v_pk_mul_f32 v[190:191], v[190:191], v[240:241]
	v_pk_fma_f32 v[26:27], v[26:27], v[82:83], v[190:191]
	v_pk_mul_f32 v[184:185], v[184:185], v[242:243]
	v_pk_fma_f32 v[28:29], v[28:29], v[84:85], v[184:185]
	v_cvt_pk_bf16_f32 v182, v30, v31
	v_cvt_pk_bf16_f32 v183, v32, v33
	v_cvt_pk_bf16_f32 v184, v26, v27
	s_nop 0
	v_cvt_pk_bf16_f32 v185, v28, v29
	s_cbranch_vccz .Lxs2_13
	flat_store_dwordx4 v[186:187], v[182:185] nt
.Lxs2_13:
	s_cbranch_vccnz .LBB0_1294
	s_nop 0
	v_pk_mul_f32 v[184:185], v[76:77], v[32:33]
	v_pk_mul_f32 v[182:183], v[74:75], v[30:31]
	v_pk_mul_f32 v[186:187], v[72:73], v[28:29]
	v_pk_mul_f32 v[188:189], v[70:71], v[26:27]
	v_cvt_pk_bf16_f32 v182, v182, v183
	v_cvt_pk_bf16_f32 v183, v184, v185
	s_nop 0
	v_cvt_pk_bf16_f32 v184, v188, v189
	v_cvt_pk_bf16_f32 v185, v186, v187
	v_lshl_add_u64 v[186:187], v[178:179], 1, s[18:19]
	flat_store_dwordx4 v[186:187], v[182:185] nt
.LBB0_1294:
	s_and_b64 vcc, exec, s[6:7]
	s_cbranch_vccnz .LBB0_1296
	v_pk_mul_f32 v[184:185], v[68:69], v[32:33]
	v_pk_mul_f32 v[182:183], v[66:67], v[30:31]
	v_lshl_add_u64 v[178:179], v[178:179], 1, s[22:23]
	v_pk_mul_f32 v[186:187], v[80:81], v[28:29]
	v_pk_mul_f32 v[188:189], v[78:79], v[26:27]
	v_cvt_pk_bf16_f32 v182, v182, v183
	v_cvt_pk_bf16_f32 v183, v184, v185
	s_nop 0
	v_cvt_pk_bf16_f32 v184, v188, v189
	v_cvt_pk_bf16_f32 v185, v186, v187
	flat_store_dwordx4 v[178:179], v[182:185] nt
.LBB0_1296:
	v_lshlrev_b32_e32 v178, 16, v42
	v_and_b32_e32 v179, 0xffff0000, v42
	v_lshlrev_b32_e32 v182, 16, v43
	v_and_b32_e32 v183, 0xffff0000, v43
	v_lshlrev_b32_e32 v184, 16, v44
	v_and_b32_e32 v185, 0xffff0000, v44
	v_lshlrev_b32_e32 v44, 16, v45
	v_and_b32_e32 v45, 0xffff0000, v45
	v_lshl_add_u64 v[42:43], v[214:215], 0, v[102:103]
	v_pk_mul_f32 v[182:183], v[182:183], v[234:235]
	v_pk_fma_f32 v[24:25], v[24:25], v[88:89], v[182:183]
	v_pk_mul_f32 v[178:179], v[178:179], v[232:233]
	v_pk_fma_f32 v[22:23], v[22:23], v[86:87], v[178:179]
	v_pk_mul_f32 v[184:185], v[184:185], v[240:241]
	v_pk_fma_f32 v[18:19], v[18:19], v[82:83], v[184:185]
	v_pk_mul_f32 v[44:45], v[44:45], v[242:243]
	v_pk_fma_f32 v[20:21], v[20:21], v[84:85], v[44:45]
	s_and_b64 vcc, exec, s[8:9]
	v_cvt_pk_bf16_f32 v182, v22, v23
	v_cvt_pk_bf16_f32 v183, v24, v25
	v_cvt_pk_bf16_f32 v184, v18, v19
	v_cvt_pk_bf16_f32 v185, v20, v21
	s_cbranch_vccz .Lxs2_14
	flat_store_dwordx4 v[176:177], v[182:185] nt
.Lxs2_14:
	s_cbranch_vccnz .LBB0_1298
	v_pk_mul_f32 v[44:45], v[76:77], v[24:25]
	v_pk_mul_f32 v[176:177], v[74:75], v[22:23]
	v_pk_mul_f32 v[178:179], v[70:71], v[18:19]
	v_cvt_pk_bf16_f32 v176, v176, v177
	v_cvt_pk_bf16_f32 v177, v44, v45
	v_lshl_add_u64 v[44:45], v[42:43], 1, s[18:19]
	v_pk_mul_f32 v[182:183], v[72:73], v[20:21]
	v_cvt_pk_bf16_f32 v178, v178, v179
	s_nop 0
	v_cvt_pk_bf16_f32 v179, v182, v183
	flat_store_dwordx4 v[44:45], v[176:179] nt
.LBB0_1298:
	s_and_b64 vcc, exec, s[6:7]
	s_cbranch_vccnz .LBB0_1300
	v_pk_mul_f32 v[176:177], v[66:67], v[22:23]
	v_pk_mul_f32 v[178:179], v[78:79], v[18:19]
	v_lshl_add_u64 v[42:43], v[42:43], 1, s[22:23]
	v_pk_mul_f32 v[44:45], v[68:69], v[24:25]
	v_pk_mul_f32 v[182:183], v[80:81], v[20:21]
	v_cvt_pk_bf16_f32 v176, v176, v177
	v_cvt_pk_bf16_f32 v177, v44, v45
	v_cvt_pk_bf16_f32 v178, v178, v179
	s_nop 0
	v_cvt_pk_bf16_f32 v179, v182, v183
	flat_store_dwordx4 v[42:43], v[176:179] nt
.LBB0_1300:
	v_lshlrev_b32_e32 v42, 16, v38
	v_and_b32_e32 v43, 0xffff0000, v38
	v_lshlrev_b32_e32 v44, 16, v39
	v_and_b32_e32 v45, 0xffff0000, v39
	v_lshlrev_b32_e32 v176, 16, v40
	v_and_b32_e32 v177, 0xffff0000, v40
	v_lshlrev_b32_e32 v40, 16, v41
	v_and_b32_e32 v41, 0xffff0000, v41
	v_lshl_add_u64 v[38:39], v[216:217], 0, v[102:103]
	v_pk_mul_f32 v[44:45], v[44:45], v[234:235]
	v_pk_fma_f32 v[16:17], v[16:17], v[88:89], v[44:45]
	v_pk_mul_f32 v[42:43], v[42:43], v[232:233]
	v_pk_fma_f32 v[14:15], v[14:15], v[86:87], v[42:43]
	v_pk_mul_f32 v[176:177], v[176:177], v[240:241]
	v_pk_fma_f32 v[10:11], v[10:11], v[82:83], v[176:177]
	v_pk_mul_f32 v[40:41], v[40:41], v[242:243]
	v_pk_fma_f32 v[12:13], v[12:13], v[84:85], v[40:41]
	s_and_b64 vcc, exec, s[8:9]
	v_cvt_pk_bf16_f32 v40, v14, v15
	v_cvt_pk_bf16_f32 v41, v16, v17
	v_cvt_pk_bf16_f32 v42, v10, v11
	v_cvt_pk_bf16_f32 v43, v12, v13
	s_cbranch_vccz .Lxs2_15
	flat_store_dwordx4 v[124:125], v[40:43] nt
.Lxs2_15:
	s_cbranch_vccnz .LBB0_1302
	s_nop 0
	v_pk_mul_f32 v[42:43], v[76:77], v[16:17]
	v_pk_mul_f32 v[40:41], v[74:75], v[14:15]
	v_pk_mul_f32 v[44:45], v[72:73], v[12:13]
	v_pk_mul_f32 v[124:125], v[70:71], v[10:11]
	v_cvt_pk_bf16_f32 v40, v40, v41
	v_cvt_pk_bf16_f32 v41, v42, v43
	s_nop 0
	v_cvt_pk_bf16_f32 v42, v124, v125
	v_cvt_pk_bf16_f32 v43, v44, v45
	v_lshl_add_u64 v[44:45], v[38:39], 1, s[18:19]
	flat_store_dwordx4 v[44:45], v[40:43] nt
.LBB0_1302:
	s_and_b64 vcc, exec, s[6:7]
	s_cbranch_vccnz .LBB0_1304
	v_pk_mul_f32 v[42:43], v[68:69], v[16:17]
	v_pk_mul_f32 v[40:41], v[66:67], v[14:15]
	v_lshl_add_u64 v[38:39], v[38:39], 1, s[22:23]
	v_pk_mul_f32 v[44:45], v[80:81], v[12:13]
	v_pk_mul_f32 v[124:125], v[78:79], v[10:11]
	v_cvt_pk_bf16_f32 v40, v40, v41
	v_cvt_pk_bf16_f32 v41, v42, v43
	s_nop 0
	v_cvt_pk_bf16_f32 v42, v124, v125
	v_cvt_pk_bf16_f32 v43, v44, v45
	flat_store_dwordx4 v[38:39], v[40:43] nt
.LBB0_1304:
	v_lshlrev_b32_e32 v38, 16, v34
	v_and_b32_e32 v39, 0xffff0000, v34
	v_lshlrev_b32_e32 v40, 16, v35
	v_and_b32_e32 v41, 0xffff0000, v35
	v_lshlrev_b32_e32 v42, 16, v36
	v_and_b32_e32 v43, 0xffff0000, v36
	v_lshlrev_b32_e32 v36, 16, v37
	v_and_b32_e32 v37, 0xffff0000, v37
	v_lshl_add_u64 v[34:35], v[122:123], 0, v[102:103]
	v_pk_mul_f32 v[40:41], v[40:41], v[234:235]
	v_pk_fma_f32 v[8:9], v[8:9], v[88:89], v[40:41]
	v_pk_mul_f32 v[38:39], v[38:39], v[232:233]
	v_pk_fma_f32 v[6:7], v[6:7], v[86:87], v[38:39]
	v_pk_mul_f32 v[42:43], v[42:43], v[240:241]
	v_pk_fma_f32 v[2:3], v[2:3], v[82:83], v[42:43]
	v_pk_mul_f32 v[36:37], v[36:37], v[242:243]
	v_pk_fma_f32 v[4:5], v[4:5], v[84:85], v[36:37]
	s_and_b64 vcc, exec, s[8:9]
	v_cvt_pk_bf16_f32 v36, v6, v7
	v_cvt_pk_bf16_f32 v37, v8, v9
	v_cvt_pk_bf16_f32 v38, v2, v3
	v_cvt_pk_bf16_f32 v39, v4, v5
	s_cbranch_vccz .Lxs2_16
	flat_store_dwordx4 v[104:105], v[36:39] nt
.Lxs2_16:
	s_cbranch_vccnz .LBB0_1324
	s_nop 0
	v_pk_mul_f32 v[38:39], v[76:77], v[8:9]
	v_pk_mul_f32 v[36:37], v[74:75], v[6:7]
	v_pk_mul_f32 v[40:41], v[72:73], v[4:5]
	v_pk_mul_f32 v[42:43], v[70:71], v[2:3]
	v_cvt_pk_bf16_f32 v36, v36, v37
	v_cvt_pk_bf16_f32 v37, v38, v39
	s_nop 0
	v_cvt_pk_bf16_f32 v38, v42, v43
	v_cvt_pk_bf16_f32 v39, v40, v41
	v_lshl_add_u64 v[40:41], v[34:35], 1, s[18:19]
	flat_store_dwordx4 v[40:41], v[36:39] nt
	s_and_b64 vcc, exec, s[6:7]
	s_cbranch_vccz .LBB0_1325

.LBB0_1325:
	v_pk_mul_f32 v[38:39], v[68:69], v[8:9]
	v_pk_mul_f32 v[36:37], v[66:67], v[6:7]
	v_lshl_add_u64 v[34:35], v[34:35], 1, s[22:23]
	v_pk_mul_f32 v[40:41], v[80:81], v[4:5]
	v_pk_mul_f32 v[42:43], v[78:79], v[2:3]
	v_cvt_pk_bf16_f32 v36, v36, v37
	v_cvt_pk_bf16_f32 v37, v38, v39
	s_nop 0
	v_cvt_pk_bf16_f32 v38, v42, v43
	v_cvt_pk_bf16_f32 v39, v40, v41
	flat_store_dwordx4 v[34:35], v[36:39] nt
	s_and_b64 vcc, exec, s[10:11]
	s_cbranch_vccnz .LBB0_1307
